# once-per-phase code warm-up (16 KB ahead) on the entry edge of the GEMM tile loops and of the setup phase main loop
# speedup vs baseline: 1.0043x; 1.0037x over previous
.LBB0_43:
	s_cmp_ge_i32 s66, s3
	v_writelane_b32 v252, s88, 5
	s_cbranch_scc1 .LBB0_104
	s_ashr_i32 s4, s21, 31
	s_add_u32 s20, s92, s21
	s_addc_u32 s21, s93, s4
	s_add_u32 s33, s14, 0x3b7c000
	s_addc_u32 s38, s15, 0
	s_add_u32 s22, s14, 0x3b40000
	s_addc_u32 s23, s15, 0
	s_add_u32 s24, s14, 0x44bc000
	s_addc_u32 s25, s15, 0
	s_add_u32 s28, s14, 0x447c000
	s_addc_u32 s29, s15, 0
	s_add_u32 s30, s20, 40
	s_addc_u32 s31, s21, 0
	s_add_u32 s34, s14, 0x3680000
	s_addc_u32 s35, s15, 0
	s_add_u32 s36, s20, 32
	s_addc_u32 s37, s21, 0
	s_add_u32 s40, s14, 0x3580000
	s_addc_u32 s41, s15, 0
	v_ashrrev_i32_e32 v143, 4, v148
	s_waitcnt vmcnt(0)
	v_and_b32_e32 v3, 15, v148
	s_add_u32 s42, s20, 24
	v_lshlrev_b32_e32 v0, 5, v143
	s_movk_i32 s39, 0x6000
	s_movk_i32 s8, 0x500
	v_and_b32_e32 v2, 16, v148
	v_cvt_f32_ubyte0_e32 v3, v3
	s_addc_u32 s43, s21, 0
	v_mad_i64_i32 v[146:147], s[4:5], v0, s39, 0
	v_mul_lo_u32 v0, v143, s8
	v_mul_f32_e32 v3, 0xbf549a78, v3
	v_cmp_eq_u32_e64 s[8:9], 0, v2
	v_and_b32_e32 v2, 8, v148
	s_add_u32 s44, s14, 0x3540000
	v_exp_f32_e32 v161, v3
	v_and_b32_e32 v3, 7, v148
	v_cmp_eq_u32_e64 s[10:11], 0, v2
	s_addc_u32 s45, s15, 0
	v_add_u32_e32 v2, 0x200, v148
	v_cvt_f32_ubyte0_e32 v3, v3
	s_add_u32 s46, s20, 16
	v_ashrrev_i32_e32 v164, 4, v2
	v_lshlrev_b32_e32 v2, 3, v148
	v_and_b32_e32 v140, 63, v148
	v_mul_f32_e32 v3, 0xbfd49a78, v3
	s_addc_u32 s47, s21, 0
	v_and_b32_e32 v154, 56, v2
	v_lshlrev_b32_e32 v2, 8, v143
	v_lshlrev_b32_e32 v151, 2, v140
	v_lshlrev_b32_e32 v155, 2, v148
	v_exp_f32_e32 v162, v3
	s_add_u32 s48, s14, 0x3040000
	v_and_b32_e32 v169, 0xfffffc00, v2
	v_and_b32_e32 v150, 60, v155
	v_ashrrev_i32_e32 v152, 6, v148
	s_addc_u32 s49, s15, 0
	v_or_b32_e32 v2, v169, v151
	v_and_b32_e32 v142, -4, v143
	v_lshlrev_b32_e32 v153, 1, v148
	s_movk_i32 s4, 0x1400
	v_lshlrev_b32_e32 v159, 2, v150
	s_movk_i32 s6, 0x140
	v_lshlrev_b32_e32 v1, 8, v152
	s_movk_i32 s16, 0x104
	v_ashrrev_i32_e32 v166, 3, v148
	s_add_u32 s54, s14, 0x3000000
	v_add_u32_e32 v170, 0x2000, v2
	v_cndmask_b32_e64 v2, 0, 1, s[12:13]
	v_mov_b32_e32 v145, 0
	v_ashrrev_i32_e32 v149, 31, v148
	v_cmp_gt_i32_e64 s[4:5], s4, v148
	v_lshlrev_b32_e32 v158, 7, v143
	v_cmp_gt_i32_e64 s[6:7], s6, v148
	v_add_u32_e32 v160, 0xfff68000, v148
	s_mov_b32 s27, 0
	v_mul_lo_u32 v163, v143, s16
	v_mul_lo_u32 v165, v164, s16
	s_addc_u32 s55, s15, 0
	v_lshlrev_b32_e32 v167, 2, v166
	v_mul_u32_u24_e32 v168, 0x104, v154
	v_mov_b32_e32 v141, v142
	s_movk_i32 s60, 0x2000
	v_add_u32_e32 v171, 0x4000, v153
	v_cmp_ne_u32_e64 s[12:13], 1, v2
	s_movk_i32 s61, 0x1000
	s_movk_i32 s62, 0x3000
	s_mov_b32 s63, 0xc000
	s_mov_b32 s64, 0x12000
	s_mov_b32 s65, 0x18000
	s_mov_b32 s67, 0x1e000
	s_movk_i32 s68, 0x7fff
	s_mov_b32 s69, 0x6c000
	s_mov_b32 s70, 0x72000
	s_mov_b32 s71, 0x78000
	s_mov_b32 s72, 0x7e000
	s_mov_b32 s73, 0x84000
	s_mov_b32 s74, 0x8a000
	s_mov_b32 s75, 0x90000
	s_mov_b32 s76, 0x96000
	s_mov_b32 s77, 0x9c000
	s_mov_b32 s78, 0xa2000
	s_mov_b32 s79, 0xa8000
	s_movk_i32 s80, 0x3ff
	s_movk_i32 s81, 0x11ff
	v_add_u32_e32 v172, v159, v0
	v_add_u32_e32 v173, v151, v1
	s_movk_i32 s82, 0x1ff
	s_movk_i32 s83, 0xc00
	s_movk_i32 s84, 0xb30
	s_movk_i32 s85, 0x2cc0
	v_lshlrev_b32_e32 v156, 2, v140
	v_mov_b32_e32 v175, 0x1800000
	v_mov_b32_e32 v176, 1
	s_movk_i32 s87, 0xfc00
	s_getpc_b64 s[94:95]
	v_mbcnt_lo_u32_b32 v254, -1, 0
	v_mbcnt_hi_u32_b32 v254, -1, v254
	v_lshlrev_b32_e32 v254, 8, v254
	global_load_dword v255, v254, s[94:95]
	global_load_dword v255, v254, s[94:95] offset:128
	s_branch .LBB0_47

.LBB0_216:
	s_add_u32 s16, s20, 0x5d52000
	s_addc_u32 s17, s21, 0
	s_lshl_b32 s6, s6, 5
	s_and_b32 s15, s6, 0x60
	s_lshl_b32 s11, s7, 13
	s_lshl_b32 s6, s15, 7
	s_add_i32 s66, s54, 0x18000
	s_mov_b64 s[18:19], 0x80
	s_add_i32 s67, s54, 0x1a000
	v_lshl_add_u64 v[0:1], v[0:1], 0, s[18:19]
	s_mov_b32 m0, s66
	s_add_u32 s8, s30, 0x40080
	s_waitcnt vmcnt(0)
	s_barrier
	global_load_lds_dwordx4 v[0:1], off
	v_lshl_add_u64 v[0:1], v[2:3], 0, s[18:19]
	s_mov_b32 m0, s67
	s_addc_u32 s9, s31, 0
	s_add_i32 s68, s54, 0x1c000
	global_load_lds_dwordx4 v[0:1], off
	v_lshl_add_u64 v[0:1], s[8:9], 0, v[136:137]
	s_mov_b32 m0, s68
	s_add_i32 s69, s54, 0x1e000
	global_load_lds_dwordx4 v[0:1], off
	v_lshl_add_u64 v[0:1], s[8:9], 0, v[138:139]
	s_mov_b32 m0, s69
	v_mov_b32_e32 v129, v137
	global_load_lds_dwordx4 v[0:1], off
	v_lshrrev_b32_e32 v1, 1, v148
	v_and_b32_e32 v1, 24, v1
	v_and_b32_e32 v0, 15, v148
	v_lshlrev_b32_e32 v2, 1, v1
	v_lshl_or_b32 v150, s7, 6, v0
	v_lshl_or_b32 v0, v0, 6, v2
	v_lshlrev_b32_e32 v2, 2, v148
	v_and_b32_e32 v2, 32, v2
	v_bitop3_b32 v151, v0, s11, v2 bitop3:0xde
	v_bitop3_b32 v0, s6, v0, v2 bitop3:0xf6
	v_mov_b32_e32 v131, v137
	v_mov_b32_e32 v133, v137
	v_mov_b32_e32 v135, v137
	s_mov_b32 s27, 0
	v_cmp_eq_u32_e64 s[6:7], 0, v148
	s_ashr_i32 s70, s2, 31
	s_ashr_i32 s71, s3, 31
	v_or_b32_e32 v152, s15, v1
	v_mov_b64_e32 v[140:141], 0x23f
	v_or_b32_e32 v153, 0x10000, v0
	v_add_u32_e32 v154, 0x10400, v0
	v_add_u32_e32 v155, 0x10800, v0
	v_add_u32_e32 v156, 0x10c00, v0
	v_or_b32_e32 v157, 0x14000, v0
	v_add_u32_e32 v158, 0x14400, v0
	v_add_u32_e32 v159, 0x14800, v0
	v_add_u32_e32 v160, 0x14c00, v0
	s_add_i32 s72, s54, 0x8000
	s_add_i32 s73, s54, 0xa000
	s_add_i32 s74, s54, 0xc000
	s_add_i32 s75, s54, 0xe000
	v_or_b32_e32 v161, 0x18000, v0
	v_add_u32_e32 v162, 0x18400, v0
	v_add_u32_e32 v163, 0x18800, v0
	v_add_u32_e32 v164, 0x18c00, v0
	v_or_b32_e32 v165, 0x1c000, v0
	v_add_u32_e32 v166, 0x1c400, v0
	v_add_u32_e32 v167, 0x1c800, v0
	v_add_u32_e32 v168, 0x1cc00, v0
	s_movk_i32 s76, 0x1660
	s_movk_i32 s77, 0xb30
	v_mov_b64_e32 v[142:143], 0x1e8481
	s_mov_b32 s78, 0
	s_barrier
	s_getpc_b64 s[94:95]
	v_mbcnt_lo_u32_b32 v254, -1, 0
	v_mbcnt_hi_u32_b32 v254, -1, v254
	v_lshlrev_b32_e32 v254, 8, v254
	global_load_dword v255, v254, s[94:95]
	global_load_dword v255, v254, s[94:95] offset:128
	s_branch .LBB0_218

.LBB0_1453:
	s_add_u32 s22, s16, 0xe3f2000
	s_addc_u32 s23, s17, 0
	s_lshl_b32 s6, s6, 5
	s_and_b32 s21, s6, 0x60
	s_lshl_b32 s11, s7, 13
	s_lshl_b32 s6, s21, 7
	s_add_i32 s72, s60, 0x18000
	s_mov_b64 s[24:25], 0x80
	s_add_i32 s73, s60, 0x1a000
	v_lshl_add_u64 v[0:1], v[0:1], 0, s[24:25]
	s_mov_b32 m0, s72
	s_add_u32 s8, s40, 0x40080
	s_waitcnt vmcnt(0)
	s_barrier
	global_load_lds_dwordx4 v[0:1], off
	v_lshl_add_u64 v[0:1], v[2:3], 0, s[24:25]
	s_mov_b32 m0, s73
	s_addc_u32 s9, s41, 0
	s_add_i32 s74, s60, 0x1c000
	global_load_lds_dwordx4 v[0:1], off
	v_lshl_add_u64 v[0:1], s[8:9], 0, v[136:137]
	s_mov_b32 m0, s74
	s_add_i32 s75, s60, 0x1e000
	global_load_lds_dwordx4 v[0:1], off
	v_lshl_add_u64 v[0:1], s[8:9], 0, v[138:139]
	s_mov_b32 m0, s75
	v_mov_b32_e32 v129, v137
	global_load_lds_dwordx4 v[0:1], off
	v_lshrrev_b32_e32 v1, 1, v150
	v_and_b32_e32 v1, 24, v1
	v_and_b32_e32 v0, 15, v150
	v_lshlrev_b32_e32 v2, 1, v1
	v_lshl_or_b32 v152, s7, 6, v0
	v_lshl_or_b32 v0, v0, 6, v2
	v_lshlrev_b32_e32 v2, 2, v150
	v_and_b32_e32 v2, 32, v2
	v_bitop3_b32 v153, v0, s11, v2 bitop3:0xde
	v_bitop3_b32 v0, s6, v0, v2 bitop3:0xf6
	v_mov_b32_e32 v131, v137
	v_mov_b32_e32 v133, v137
	v_mov_b32_e32 v135, v137
	s_mov_b32 s27, 0
	v_cmp_eq_u32_e64 s[6:7], 0, v150
	s_ashr_i32 s76, s2, 31
	s_ashr_i32 s77, s3, 31
	v_or_b32_e32 v154, s21, v1
	v_mov_b64_e32 v[140:141], 0xbf
	v_or_b32_e32 v155, 0x10000, v0
	v_add_u32_e32 v156, 0x10400, v0
	v_add_u32_e32 v157, 0x10800, v0
	v_add_u32_e32 v158, 0x10c00, v0
	v_or_b32_e32 v159, 0x14000, v0
	v_add_u32_e32 v160, 0x14400, v0
	v_add_u32_e32 v161, 0x14800, v0
	v_add_u32_e32 v162, 0x14c00, v0
	s_add_i32 s78, s60, 0x8000
	s_add_i32 s79, s60, 0xa000
	s_add_i32 s80, s60, 0xc000
	s_add_i32 s81, s60, 0xe000
	v_or_b32_e32 v163, 0x18000, v0
	v_add_u32_e32 v164, 0x18400, v0
	v_add_u32_e32 v165, 0x18800, v0
	v_add_u32_e32 v166, 0x18c00, v0
	v_or_b32_e32 v167, 0x1c000, v0
	v_add_u32_e32 v168, 0x1c400, v0
	v_add_u32_e32 v169, 0x1c800, v0
	v_add_u32_e32 v170, 0x1cc00, v0
	s_mov_b64 s[28:29], 0x58000
	v_mov_b64_e32 v[142:143], 0x1e8481
	s_mov_b32 s82, 0
	s_barrier
	s_getpc_b64 s[94:95]
	v_mbcnt_lo_u32_b32 v254, -1, 0
	v_mbcnt_hi_u32_b32 v254, -1, v254
	v_lshlrev_b32_e32 v254, 8, v254
	global_load_dword v255, v254, s[94:95]
	global_load_dword v255, v254, s[94:95] offset:128
	s_branch .LBB0_1455

.LBB0_1724:
	s_add_u32 s14, s10, 0x5d52000
	s_addc_u32 s15, s11, 0
	s_lshl_b32 s6, s6, 5
	s_and_b32 s11, s6, 0x60
	s_lshl_b32 s10, s7, 13
	s_lshl_b32 s6, s11, 7
	s_add_i32 s67, s45, 0x18000
	s_mov_b64 s[18:19], 0x80
	s_add_i32 s72, s45, 0x1a000
	v_lshl_add_u64 v[0:1], v[0:1], 0, s[18:19]
	s_mov_b32 m0, s67
	s_add_u32 s8, s48, 0x40080
	s_waitcnt vmcnt(0)
	s_barrier
	global_load_lds_dwordx4 v[0:1], off
	v_lshl_add_u64 v[0:1], v[2:3], 0, s[18:19]
	s_mov_b32 m0, s72
	s_addc_u32 s9, s49, 0
	s_add_i32 s73, s45, 0x1c000
	global_load_lds_dwordx4 v[0:1], off
	v_lshl_add_u64 v[0:1], s[8:9], 0, v[136:137]
	s_mov_b32 m0, s73
	s_add_i32 s74, s45, 0x1e000
	global_load_lds_dwordx4 v[0:1], off
	v_lshl_add_u64 v[0:1], s[8:9], 0, v[138:139]
	s_mov_b32 m0, s74
	v_mov_b32_e32 v129, v137
	global_load_lds_dwordx4 v[0:1], off
	v_lshrrev_b32_e32 v1, 1, v59
	v_and_b32_e32 v1, 24, v1
	v_and_b32_e32 v0, 15, v59
	v_lshlrev_b32_e32 v2, 1, v1
	v_lshl_or_b32 v151, s7, 6, v0
	v_lshl_or_b32 v0, v0, 6, v2
	v_lshlrev_b32_e32 v2, 2, v59
	v_and_b32_e32 v2, 32, v2
	v_bitop3_b32 v152, v0, s10, v2 bitop3:0xde
	v_bitop3_b32 v0, s6, v0, v2 bitop3:0xf6
	v_mov_b32_e32 v131, v137
	v_mov_b32_e32 v133, v137
	v_mov_b32_e32 v135, v137
	s_mov_b32 s21, 0
	v_cmp_eq_u32_e64 s[6:7], 0, v59
	s_ashr_i32 s75, s2, 31
	s_ashr_i32 s76, s3, 31
	v_or_b32_e32 v153, s11, v1
	v_mov_b64_e32 v[140:141], 0x2ff
	v_or_b32_e32 v154, 0x10000, v0
	v_add_u32_e32 v155, 0x10400, v0
	v_add_u32_e32 v156, 0x10800, v0
	v_add_u32_e32 v157, 0x10c00, v0
	v_or_b32_e32 v158, 0x14000, v0
	v_add_u32_e32 v159, 0x14400, v0
	v_add_u32_e32 v160, 0x14800, v0
	v_add_u32_e32 v161, 0x14c00, v0
	s_add_i32 s77, s45, 0x8000
	s_add_i32 s78, s45, 0xa000
	s_add_i32 s79, s45, 0xc000
	s_add_i32 s80, s45, 0xe000
	v_or_b32_e32 v162, 0x18000, v0
	v_add_u32_e32 v163, 0x18400, v0
	v_add_u32_e32 v164, 0x18800, v0
	v_add_u32_e32 v165, 0x18c00, v0
	v_or_b32_e32 v166, 0x1c000, v0
	v_add_u32_e32 v167, 0x1c400, v0
	v_add_u32_e32 v168, 0x1c800, v0
	v_add_u32_e32 v169, 0x1cc00, v0
	s_movk_i32 s81, 0x1000
	s_mov_b64 s[22:23], 0x100000
	s_mov_b64 s[24:25], 0x120000
	s_mov_b64 s[26:27], 0x140000
	s_mov_b64 s[28:29], 0x160000
	v_mov_b64_e32 v[142:143], 0x1e8481
	s_mov_b32 s82, 0
	s_barrier
	s_getpc_b64 s[94:95]
	v_mbcnt_lo_u32_b32 v254, -1, 0
	v_mbcnt_hi_u32_b32 v254, -1, v254
	v_lshlrev_b32_e32 v254, 8, v254
	global_load_dword v255, v254, s[94:95]
	global_load_dword v255, v254, s[94:95] offset:128
	s_branch .LBB0_1726

.LBB0_2114:
	s_add_u32 s18, s10, 0x5d52000
	s_addc_u32 s19, s11, 0
	s_lshl_b32 s6, s6, 5
	s_and_b32 s10, s6, 0x60
	s_lshl_b32 s6, s10, 7
	s_add_i32 s62, s55, 0x18000
	s_mov_b64 s[20:21], 0x80
	s_add_i32 s63, s55, 0x1a000
	v_lshl_add_u64 v[0:1], v[0:1], 0, s[20:21]
	s_mov_b32 m0, s62
	s_add_u32 s8, s26, 0x40080
	s_waitcnt vmcnt(0)
	s_barrier
	global_load_lds_dwordx4 v[0:1], off
	v_lshl_add_u64 v[0:1], v[2:3], 0, s[20:21]
	s_mov_b32 m0, s63
	s_addc_u32 s9, s27, 0
	s_add_i32 s64, s55, 0x1c000
	global_load_lds_dwordx4 v[0:1], off
	v_lshl_add_u64 v[0:1], s[8:9], 0, v[102:103]
	s_mov_b32 m0, s64
	s_add_i32 s65, s55, 0x1e000
	global_load_lds_dwordx4 v[0:1], off
	v_lshl_add_u64 v[0:1], s[8:9], 0, v[104:105]
	s_mov_b32 m0, s65
	s_mul_i32 s8, s7, 48
	global_load_lds_dwordx4 v[0:1], off
	v_lshrrev_b32_e32 v1, 1, v59
	v_and_b32_e32 v1, 24, v1
	v_and_b32_e32 v0, 15, v59
	v_lshlrev_b32_e32 v2, 1, v1
	v_or_b32_e32 v117, s8, v0
	v_lshl_or_b32 v0, v0, 6, v2
	v_lshlrev_b32_e32 v2, 2, v59
	s_mulk_i32 s7, 0x1800
	v_and_b32_e32 v2, 32, v2
	v_bitop3_b32 v118, v0, s7, v2 bitop3:0xde
	v_bitop3_b32 v0, s6, v0, v2 bitop3:0xf6
	v_mov_b32_e32 v97, v103
	v_mov_b32_e32 v99, v103
	v_mov_b32_e32 v101, v103
	s_mov_b32 s23, 0
	v_cmp_eq_u32_e64 s[6:7], 0, v59
	s_ashr_i32 s66, s3, 31
	s_ashr_i32 s67, s2, 31
	v_or_b32_e32 v119, s10, v1
	v_mov_b64_e32 v[106:107], 0x300
	v_mov_b64_e32 v[108:109], 0x2ff
	v_or_b32_e32 v120, 0x10000, v0
	v_add_u32_e32 v121, 0x10400, v0
	v_add_u32_e32 v122, 0x10800, v0
	v_add_u32_e32 v123, 0x10c00, v0
	v_or_b32_e32 v124, 0x14000, v0
	v_add_u32_e32 v125, 0x14400, v0
	v_add_u32_e32 v126, 0x14800, v0
	v_add_u32_e32 v127, 0x14c00, v0
	s_add_i32 s68, s55, 0x8000
	s_add_i32 s69, s55, 0xa000
	s_add_i32 s70, s55, 0xc000
	v_or_b32_e32 v128, 0x18000, v0
	v_add_u32_e32 v129, 0x18400, v0
	v_add_u32_e32 v130, 0x18800, v0
	v_add_u32_e32 v131, 0x18c00, v0
	v_or_b32_e32 v132, 0x1c000, v0
	v_add_u32_e32 v133, 0x1c400, v0
	v_add_u32_e32 v134, 0x1c800, v0
	v_add_u32_e32 v135, 0x1cc00, v0
	s_movk_i32 s71, 0x1660
	s_movk_i32 s72, 0xb30
	v_mov_b64_e32 v[110:111], 0x1e8481
	s_mov_b32 s73, 0
	s_barrier
	s_getpc_b64 s[94:95]
	v_mbcnt_lo_u32_b32 v254, -1, 0
	v_mbcnt_hi_u32_b32 v254, -1, v254
	v_lshlrev_b32_e32 v254, 8, v254
	global_load_dword v255, v254, s[94:95]
	global_load_dword v255, v254, s[94:95] offset:128
	s_branch .LBB0_2116

.LBB0_3210:
	s_add_u32 s18, s18, 0xe3f2000
	s_addc_u32 s19, s19, 0
	s_lshl_b32 s6, s6, 5
	s_and_b32 s10, s6, 0x60
	s_lshl_b32 s6, s10, 7
	s_add_i32 s73, s61, 0x18000
	s_mov_b64 s[22:23], 0x80
	s_add_i32 s74, s61, 0x1a000
	v_lshl_add_u64 v[2:3], v[2:3], 0, s[22:23]
	s_mov_b32 m0, s73
	s_add_u32 s8, s40, 0x40080
	s_waitcnt vmcnt(0)
	s_barrier
	global_load_lds_dwordx4 v[2:3], off
	v_lshl_add_u64 v[0:1], v[0:1], 0, s[22:23]
	s_mov_b32 m0, s74
	s_addc_u32 s9, s41, 0
	s_add_i32 s75, s61, 0x1c000
	global_load_lds_dwordx4 v[0:1], off
	v_lshl_add_u64 v[0:1], s[8:9], 0, v[102:103]
	s_mov_b32 m0, s75
	s_add_i32 s76, s61, 0x1e000
	global_load_lds_dwordx4 v[0:1], off
	v_lshl_add_u64 v[0:1], s[8:9], 0, v[104:105]
	s_mov_b32 m0, s76
	s_mul_i32 s8, s7, 48
	global_load_lds_dwordx4 v[0:1], off
	v_lshrrev_b32_e32 v1, 1, v74
	v_and_b32_e32 v1, 24, v1
	v_and_b32_e32 v0, 15, v74
	v_lshlrev_b32_e32 v2, 1, v1
	v_or_b32_e32 v119, s8, v0
	v_lshl_or_b32 v0, v0, 6, v2
	v_lshlrev_b32_e32 v2, 2, v74
	s_mulk_i32 s7, 0x1800
	v_and_b32_e32 v2, 32, v2
	v_bitop3_b32 v120, v0, s7, v2 bitop3:0xde
	v_bitop3_b32 v0, s6, v0, v2 bitop3:0xf6
	v_mov_b32_e32 v97, v103
	v_mov_b32_e32 v99, v103
	v_mov_b32_e32 v101, v103
	s_mov_b32 s25, 0
	v_cmp_eq_u32_e64 s[6:7], 0, v74
	s_ashr_i32 s77, s3, 31
	s_ashr_i32 s78, s2, 31
	v_or_b32_e32 v121, s10, v1
	v_mov_b64_e32 v[106:107], 0x100
	v_mov_b64_e32 v[108:109], 0xff
	v_or_b32_e32 v122, 0x10000, v0
	v_add_u32_e32 v123, 0x10400, v0
	v_add_u32_e32 v124, 0x10800, v0
	v_add_u32_e32 v125, 0x10c00, v0
	v_or_b32_e32 v126, 0x14000, v0
	v_add_u32_e32 v127, 0x14400, v0
	v_add_u32_e32 v128, 0x14800, v0
	v_add_u32_e32 v129, 0x14c00, v0
	s_add_i32 s79, s61, 0x8000
	s_add_i32 s80, s61, 0xa000
	s_add_i32 s81, s61, 0xc000
	v_or_b32_e32 v130, 0x18000, v0
	v_add_u32_e32 v131, 0x18400, v0
	v_add_u32_e32 v132, 0x18800, v0
	v_add_u32_e32 v133, 0x18c00, v0
	v_or_b32_e32 v134, 0x1c000, v0
	v_add_u32_e32 v135, 0x1c400, v0
	v_add_u32_e32 v136, 0x1c800, v0
	v_add_u32_e32 v137, 0x1cc00, v0
	s_mov_b64 s[26:27], 0x8000
	s_mov_b64 s[28:29], 0x10000
	s_mov_b64 s[30:31], 0x30000
	s_mov_b64 s[34:35], 0x38000
	v_mov_b64_e32 v[110:111], 0x1e8481
	s_mov_b32 s82, 0
	s_barrier
	s_getpc_b64 s[94:95]
	v_mbcnt_lo_u32_b32 v254, -1, 0
	v_mbcnt_hi_u32_b32 v254, -1, v254
	v_lshlrev_b32_e32 v254, 8, v254
	global_load_dword v255, v254, s[94:95]
	global_load_dword v255, v254, s[94:95] offset:128
	s_branch .LBB0_3212

.LBB0_3360:
	s_add_u32 s14, s10, 0x5d52000
	s_addc_u32 s15, s11, 0
	s_lshl_b32 s6, s6, 5
	s_and_b32 s11, s6, 0x60
	s_lshl_b32 s10, s7, 13
	s_lshl_b32 s6, s11, 7
	s_add_i32 s71, s45, 0x18000
	s_mov_b64 s[18:19], 0x80
	s_add_i32 s72, s45, 0x1a000
	v_lshl_add_u64 v[0:1], v[0:1], 0, s[18:19]
	s_mov_b32 m0, s71
	s_add_u32 s8, s48, 0x40080
	s_waitcnt vmcnt(0)
	s_barrier
	global_load_lds_dwordx4 v[0:1], off
	v_lshl_add_u64 v[0:1], v[2:3], 0, s[18:19]
	s_mov_b32 m0, s72
	s_addc_u32 s9, s49, 0
	s_add_i32 s73, s45, 0x1c000
	global_load_lds_dwordx4 v[0:1], off
	v_lshl_add_u64 v[0:1], s[8:9], 0, v[136:137]
	s_mov_b32 m0, s73
	s_add_i32 s74, s45, 0x1e000
	global_load_lds_dwordx4 v[0:1], off
	v_lshl_add_u64 v[0:1], s[8:9], 0, v[138:139]
	s_mov_b32 m0, s74
	v_mov_b32_e32 v129, v137
	global_load_lds_dwordx4 v[0:1], off
	v_lshrrev_b32_e32 v1, 1, v59
	v_and_b32_e32 v1, 24, v1
	v_and_b32_e32 v0, 15, v59
	v_lshlrev_b32_e32 v2, 1, v1
	v_lshl_or_b32 v151, s7, 6, v0
	v_lshl_or_b32 v0, v0, 6, v2
	v_lshlrev_b32_e32 v2, 2, v59
	v_and_b32_e32 v2, 32, v2
	v_bitop3_b32 v152, v0, s10, v2 bitop3:0xde
	v_bitop3_b32 v0, s6, v0, v2 bitop3:0xf6
	v_mov_b32_e32 v131, v137
	v_mov_b32_e32 v133, v137
	v_mov_b32_e32 v135, v137
	s_mov_b32 s21, 0
	v_cmp_eq_u32_e64 s[6:7], 0, v59
	s_ashr_i32 s75, s3, 31
	s_ashr_i32 s76, s2, 31
	v_or_b32_e32 v153, s11, v1
	v_mov_b64_e32 v[140:141], 0x2ff
	v_or_b32_e32 v154, 0x10000, v0
	v_add_u32_e32 v155, 0x10400, v0
	v_add_u32_e32 v156, 0x10800, v0
	v_add_u32_e32 v157, 0x10c00, v0
	v_or_b32_e32 v158, 0x14000, v0
	v_add_u32_e32 v159, 0x14400, v0
	v_add_u32_e32 v160, 0x14800, v0
	v_add_u32_e32 v161, 0x14c00, v0
	s_add_i32 s77, s45, 0x8000
	s_add_i32 s78, s45, 0xa000
	s_add_i32 s79, s45, 0xc000
	s_add_i32 s80, s45, 0xe000
	v_or_b32_e32 v162, 0x18000, v0
	v_add_u32_e32 v163, 0x18400, v0
	v_add_u32_e32 v164, 0x18800, v0
	v_add_u32_e32 v165, 0x18c00, v0
	v_or_b32_e32 v166, 0x1c000, v0
	v_add_u32_e32 v167, 0x1c400, v0
	v_add_u32_e32 v168, 0x1c800, v0
	v_add_u32_e32 v169, 0x1cc00, v0
	s_movk_i32 s81, 0x1000
	s_mov_b64 s[22:23], 0x100000
	s_mov_b64 s[24:25], 0x120000
	s_mov_b64 s[26:27], 0x140000
	s_mov_b64 s[28:29], 0x160000
	v_mov_b64_e32 v[142:143], 0x1e8481
	s_mov_b32 s82, 0
	s_barrier
	s_getpc_b64 s[94:95]
	v_mbcnt_lo_u32_b32 v254, -1, 0
	v_mbcnt_hi_u32_b32 v254, -1, v254
	v_lshlrev_b32_e32 v254, 8, v254
	global_load_dword v255, v254, s[94:95]
	global_load_dword v255, v254, s[94:95] offset:128
	s_branch .LBB0_3362
